# scan producers: chunk offsets folded into VGPR offsets, per-parity LDS address constants, both RK stores under one EXEC switch (fewer issue slots on the producer SIMDs)
# speedup vs baseline: 1.1034x; 1.0017x over previous
; #define LAS __attribute__((address_space(3)))
; DI unsigned pk2(float lo, float hi) { f32x2 v = {lo, hi}; bf16x2_t b = __builtin_convertvector(v, bf16x2_t); return __builtin_bit_cast(unsigned, b); }
; DI float row16_sum(float v) { v += dpp_f<0xB1>(v); v += dpp_f<0x4E>(v); v += dpp_f<0x141>(v); v += dpp_f<0x140>(v); return v; }
; DI void rwkv_scan_phase(int wv, const Params& P, LAS unsigned char* lds) {
;     ...
;             const int ch = h * 64 + lane;
;             const float kkw = P.in[35][ch], kaw = P.in[36][ch], rkw = P.in[37][ch];
;             const int hf = lane >> 5, c2 = lane & 31, chp = h * 64 + 2 * c2;
;             const f32x2 kkw2 = *(const f32x2*)(P.in[35] + chp), kaw2 = *(const f32x2*)(P.in[36] + chp), rkw2 = *(const f32x2*)(P.in[37] + chp);
;             unsigned gk[3], ga[3], gr[3], gl[3]; float gv[3];
;     ...
;             RW_LOADG(0)
; #pragma unroll 1
;             for (int ck = -1; ck <= nck; ++ck) {
;                 {
;                     if (ck >= 1) { const LAS float* yb = ybuf + ((ck - 1) & 1) * RW_T * 128;
; #pragma unroll 2
;                         for (int it = pw; it < 64; it += 6) { const float y = row16_sum(yb[it * 64 + lane]);
;                             const float y0 = __builtin_bit_cast(float, __builtin_amdgcn_readlane(__builtin_bit_cast(int, y), 0)), y1 = __builtin_bit_cast(float, __builtin_amdgcn_readlane(__builtin_bit_cast(int, y), 16)),
;                                         y2 = __builtin_bit_cast(float, __builtin_amdgcn_readlane(__builtin_bit_cast(int, y), 32)), y3 = __builtin_bit_cast(float, __builtin_amdgcn_readlane(__builtin_bit_cast(int, y), 48));
;                             if (lane == 0) { u32x2 w; w.x = pk2(y0, y1); w.y = pk2(y2, y3); *(u32x2*)(YS + ((size_t)b * SEQ + (ck - 1) * RW_T + (it >> 1)) * 1024 + h * 64 + rg * 8 + (it & 1) * 4) = w; } } }
;                     if (ck + 1 < nck) { const int cn = ck + 1, buf = cn & 1;
; #pragma unroll
;                         for (int i = 0; i < 3; ++i) { const int pp = pw + 6 * i; if (pp < 16) { const int tt = 2 * pp + hf; const size_t row = (size_t)b * SEQ + cn * RW_T + tt;
.LBB0_3185:
	s_andn2_saveexec_b64 s[40:41], s[20:21]
	s_cbranch_execz .LBB0_3174
	v_readfirstlane_b32 s55, v41
	s_and_b32 s66, s55, 2
	s_cmp_lg_u32 s66, 0
	s_cbranch_scc1 .Lprod_flusher
	s_lshr_b32 s66, s55, 1
	s_and_b32 s55, s55, 1
	s_or_b32 s55, s55, s66
	s_and_b32 s67, s46, 7
	s_bfe_u32 s59, s46, 0x40003
	s_lshr_b32 s60, s46, 7
	s_lshl_b32 s60, s60, 13
	s_lshl_b32 s66, s55, 2
	s_add_i32 s60, s60, s66
	v_mbcnt_lo_u32_b32 v0, -1, 0
	v_mbcnt_hi_u32_b32 v0, -1, v0
	v_and_b32_e32 v1, 31, v0
	v_lshrrev_b32_e32 v31, 5, v0
	s_lshl_b32 s61, s59, 6
	v_lshl_add_u32 v32, v1, 1, s61
	v_lshlrev_b32_e32 v33, 2, v32
	global_load_dwordx2 v[4:5], v33, s[24:25]
	global_load_dwordx2 v[6:7], v33, s[26:27]
	global_load_dwordx2 v[8:9], v33, s[38:39]
	v_add_u32_e32 v34, s60, v31
	v_lshlrev_b32_e32 v35, 11, v34
	v_lshl_add_u32 v12, v32, 1, v35
	v_add_u32_e32 v13, 0x1000, v12
	s_lshl_b32 s66, s55, 2
	v_add_u32_e32 v37, s66, v31
	v_mul_u32_u24_e32 v2, 0xc00, v37
	v_lshl_add_u32 v2, v1, 3, v2
	s_lshl_b32 s66, s59, 2
	v_lshl_add_u32 v10, v34, 6, s66
	v_or_b32_e32 v38, s67, v1
	v_cmp_eq_u32_e64 s[42:43], 0, v38
	v_mov_b32_e32 v52, v2
	v_lshl_add_u32 v53, v1, 3, v52
	v_mov_b32_e32 v54, 0x1e000
	v_lshl_add_u32 v54, v1, 3, v54
	v_add_u32_e32 v55, 0xc000, v2
	v_lshl_add_u32 v56, v1, 3, v55
	v_add_u32_e32 v57, 0x100, v54
	s_mov_b32 s57, -1
	s_mov_b32 s67, 0
	s_waitcnt vmcnt(0)
	v_add_u32_e32 v14, s67, v12
	v_add_u32_e32 v15, s67, v13
	global_load_dword v44, v14, s[28:29]
	global_load_dword v48, v15, s[28:29]
	global_load_dword v45, v14, s[34:35]
	global_load_dword v49, v15, s[34:35]
	global_load_dword v46, v14, s[22:23]
	global_load_dword v50, v15, s[22:23]
	global_load_dword v47, v14, s[36:37]
	global_load_dword v51, v15, s[36:37]
	global_load_dword v0, v14, s[22:23] offset:-2048
	global_load_dword v40, v15, s[22:23] offset:-2048
	s_mov_b32 s67, 0x8000
	v_add_u32_e32 v14, s67, v12
	v_add_u32_e32 v15, s67, v13
	global_load_dword v24, v14, s[28:29]
	global_load_dword v28, v15, s[28:29]
	global_load_dword v25, v14, s[34:35]
	global_load_dword v29, v15, s[34:35]
	global_load_dword v26, v14, s[22:23]
	global_load_dword v30, v15, s[22:23]
	global_load_dword v27, v14, s[36:37]
	global_load_dword v31, v15, s[36:37]
	global_load_dword v3, v14, s[22:23] offset:-2048
	global_load_dword v43, v15, s[22:23] offset:-2048
.Lprod_loop:
.Lprod_half_0:
	s_cmp_gt_i32 s57, 0x1fe
	s_cbranch_scc1 .Lprod_sync_0
	s_add_i32 s67, s57, 1
	s_lshl_b32 s60, s67, 10
	v_add_u32_e32 v58, s60, v10
	s_cmp_gt_i32 s57, 0x1fd
	s_cbranch_scc1 .Lprod_w0_0
	s_waitcnt vmcnt(10)
	s_branch .Lprod_wd_0

; #define LAS __attribute__((address_space(3)))
; DI float bflo(unsigned u) { return __uint_as_float(u << 16); }
; DI float bfhi(unsigned u) { return __uint_as_float(u & 0xffff0000u); }
; template <int CTRL> DI float dpp_f(float v) { return __builtin_bit_cast(float, __builtin_amdgcn_update_dpp(0, __builtin_bit_cast(int, v), CTRL, 0xf, 0xf, true)); }
; DI void rwkv_scan_phase(int wv, const Params& P, LAS unsigned char* lds) {
;     ...
;                         for (int i = 0; i < 3; ++i) { const int pp = pw + 6 * i; if (pp < 16) { const int tt = 2 * pp + hf; const size_t row = (size_t)b * SEQ + cn * RW_T + tt;
;                             const f32x2 k = {bflo(gk[i]), bfhi(gk[i])}, a = {bflo(ga[i]), bfhi(ga[i])}, r = {bflo(gr[i]), bfhi(gr[i])};
;                             const h16x2 lh = __builtin_bit_cast(h16x2, gl[i]);
;                             const f32x2 kr = k * kkw2, kp = k * ((a - 1.f) * kaw2 + 1.f);
;                             const float sp = kr[0] * kr[0] + kr[1] * kr[1], rp = r[0] * kp[0] * rkw2[0] + r[1] * kp[1] * rkw2[1];
;                             const bool odd = lane & 1;
;                             float red = (odd ? rp : sp) + dpp_f<0xB1>(odd ? sp : rp);
;                             red += dpp_f<0x4E>(red); red += dpp_f<0x124>(red); red += dpp_f<0x128>(red);
;                             { auto x = __builtin_amdgcn_permlane16_swap(__float_as_uint(red), __float_as_uint(red), false, false); red = __uint_as_float(x[0]) + __uint_as_float(x[1]); }
;                             const float oth = dpp_f<0xB1>(red); const float ss = odd ? oth : red, rks = odd ? red : oth;
;                             const f32x2 kk = kr * __builtin_amdgcn_rsqf(fmaxf(ss, 1e-24f));
;                             LAS float* d = stg + ((buf * RW_T + tt) * 5) * 64 + 2 * c2;
;                             *(LAS f32x2*)(d) = -kk; *(LAS f32x2*)(d + 64) = (f32x2){__expf((float)lh[0]), __expf((float)lh[1])}; *(LAS f32x2*)(d + 128) = kk * a; *(LAS f32x2*)(d + 192) = kp; *(LAS f32x2*)(d + 256) = r;
;                             if (rg == 0 && c2 == 0) RK[row * 16 + h] = rks;
;                             if (c2 < 8) vst[(buf * RW_T + tt) * 8 + c2] = gv[i]; } }
;                         if (ck + 2 < nck) { RW_LOADG(ck + 2) } }
.Lprod_wd_0:
	v_lshlrev_b32_e32 v64, 16, v45
	v_and_b32_e32 v65, 0xffff0000, v45
	v_pk_add_f32 v[72:73], v[64:65], -1.0 op_sel_hi:[1,0]
	v_lshlrev_b32_e32 v66, 16, v44
	v_and_b32_e32 v67, 0xffff0000, v44
	v_pk_fma_f32 v[72:73], v[6:7], v[72:73], 1.0 op_sel_hi:[1,1,0]
	v_and_b32_e32 v69, 0xffff0000, v46
	v_pk_mul_f32 v[70:71], v[4:5], v[66:67]
	v_pk_mul_f32 v[66:67], v[72:73], v[66:67]
	v_lshlrev_b32_e32 v68, 16, v46
	v_mul_f32_e32 v75, v67, v69
	v_pk_mul_f32 v[72:73], v[70:71], v[70:71]
	v_mul_f32_e32 v74, v66, v68
	v_mul_f32_e32 v75, v9, v75
	v_add_f32_e32 v76, v72, v73
	v_fmac_f32_e32 v75, v8, v74
	v_cndmask_b32_e64 v74, v75, v76, s[8:9]
	v_cndmask_b32_e64 v76, v76, v75, s[8:9]
	v_cvt_f32_f16_e32 v77, v47
	v_cvt_f32_f16_sdwa v78, v47 dst_sel:DWORD dst_unused:UNUSED_PAD src0_sel:WORD_1
	v_add_f32_dpp v76, v76, v74 quad_perm:[1,0,3,2] row_mask:0xf bank_mask:0xf bound_ctrl:1
	v_mul_f32_e32 v77, 0x3fb8aa3b, v77
	s_nop 0
	v_add_f32_dpp v76, v76, v76 quad_perm:[2,3,0,1] row_mask:0xf bank_mask:0xf bound_ctrl:1
	v_exp_f32_e32 v72, v77
	v_mul_f32_e32 v77, 0x3fb8aa3b, v78
	v_add_f32_dpp v76, v76, v76 row_ror:4 row_mask:0xf bank_mask:0xf bound_ctrl:1
	v_exp_f32_e32 v73, v77
	s_nop 0
	v_add_f32_dpp v76, v76, v76 row_ror:8 row_mask:0xf bank_mask:0xf bound_ctrl:1
	v_mov_b32_e32 v74, v76
	s_nop 1
	v_permlane16_swap_b32_e32 v76, v74
	v_add_f32_e32 v76, v76, v74
	s_nop 1
	v_mov_b32_dpp v74, v76 quad_perm:[1,0,3,2] row_mask:0xf bank_mask:0xf bound_ctrl:1
	v_cndmask_b32_e64 v75, v74, v76, s[8:9]
	v_max_f32_e32 v75, v75, v75
	v_max_f32_e32 v75, 0x179abe15, v75
	v_rsq_f32_e32 v42, v75
	v_cndmask_b32_e64 v76, v76, v74, s[8:9]
	s_nop 0
	v_pk_mul_f32 v[70:71], v[70:71], v[42:43] op_sel_hi:[1,0] neg_lo:[0,1] neg_hi:[0,1]
	ds_write_b64 v52, v[72:73] offset:512
	s_nop 0
	v_pk_mul_f32 v[64:65], v[70:71], v[64:65] neg_lo:[1,0] neg_hi:[1,0]
	v_mov_b32_e32 v72, v71
	v_lshlrev_b32_e32 v71, 16, v0
	ds_write_b64 v52, v[64:65] offset:768
	v_and_b32_e32 v73, 0xffff0000, v0
	ds_write_b128 v53, v[70:73]
	v_mov_b32_e32 v60, v76
	v_lshlrev_b32_e32 v64, 16, v49
	v_and_b32_e32 v65, 0xffff0000, v49
	v_pk_add_f32 v[72:73], v[64:65], -1.0 op_sel_hi:[1,0]
	v_lshlrev_b32_e32 v66, 16, v48
	v_and_b32_e32 v67, 0xffff0000, v48
	v_pk_fma_f32 v[72:73], v[6:7], v[72:73], 1.0 op_sel_hi:[1,1,0]
	v_and_b32_e32 v69, 0xffff0000, v50
	v_pk_mul_f32 v[70:71], v[4:5], v[66:67]
	v_pk_mul_f32 v[66:67], v[72:73], v[66:67]
	v_lshlrev_b32_e32 v68, 16, v50
	v_mul_f32_e32 v75, v67, v69
	v_pk_mul_f32 v[72:73], v[70:71], v[70:71]
	v_mul_f32_e32 v74, v66, v68
	v_mul_f32_e32 v75, v9, v75
	v_add_f32_e32 v76, v72, v73
	v_fmac_f32_e32 v75, v8, v74
	v_cndmask_b32_e64 v74, v75, v76, s[8:9]
	v_cndmask_b32_e64 v76, v76, v75, s[8:9]
	v_cvt_f32_f16_e32 v77, v51
	v_cvt_f32_f16_sdwa v78, v51 dst_sel:DWORD dst_unused:UNUSED_PAD src0_sel:WORD_1
	v_add_f32_dpp v76, v76, v74 quad_perm:[1,0,3,2] row_mask:0xf bank_mask:0xf bound_ctrl:1
	v_mul_f32_e32 v77, 0x3fb8aa3b, v77
	s_nop 0
	v_add_f32_dpp v76, v76, v76 quad_perm:[2,3,0,1] row_mask:0xf bank_mask:0xf bound_ctrl:1
	v_exp_f32_e32 v72, v77
	v_mul_f32_e32 v77, 0x3fb8aa3b, v78
	v_add_f32_dpp v76, v76, v76 row_ror:4 row_mask:0xf bank_mask:0xf bound_ctrl:1
	v_exp_f32_e32 v73, v77
	s_nop 0
	v_add_f32_dpp v76, v76, v76 row_ror:8 row_mask:0xf bank_mask:0xf bound_ctrl:1
	v_mov_b32_e32 v74, v76
	s_nop 1
	v_permlane16_swap_b32_e32 v76, v74
	v_add_f32_e32 v76, v76, v74
	s_nop 1
	v_mov_b32_dpp v74, v76 quad_perm:[1,0,3,2] row_mask:0xf bank_mask:0xf bound_ctrl:1
	v_cndmask_b32_e64 v75, v74, v76, s[8:9]
	v_max_f32_e32 v75, v75, v75
	v_max_f32_e32 v75, 0x179abe15, v75
	v_rsq_f32_e32 v42, v75
	v_cndmask_b32_e64 v76, v76, v74, s[8:9]
	s_nop 0
	v_pk_mul_f32 v[70:71], v[70:71], v[42:43] op_sel_hi:[1,0] neg_lo:[0,1] neg_hi:[0,1]
	ds_write_b64 v52, v[72:73] offset:6656
	s_nop 0
	v_pk_mul_f32 v[64:65], v[70:71], v[64:65] neg_lo:[1,0] neg_hi:[1,0]
	v_mov_b32_e32 v72, v71
	v_lshlrev_b32_e32 v71, 16, v40
	ds_write_b64 v52, v[64:65] offset:6912
	v_and_b32_e32 v73, 0xffff0000, v40
	ds_write_b128 v53, v[70:73] offset:6144
	v_mov_b32_e32 v61, v76
	s_mov_b64 exec, s[42:43]
	global_store_dword v58, v60, s[50:51]
	global_store_dword v58, v61, s[50:51] offset:128
	s_mov_b64 exec, -1
	s_cmp_lg_u32 s55, 3
	s_cbranch_scc1 .Lprod_no_rl_0
	s_mov_b32 exec_lo, 0
	ds_write_b64 v54, v[68:69]
	s_mov_b64 exec, -1
.Lprod_no_rl_0:
	s_cmp_gt_i32 s57, 0x1fc
	s_cbranch_scc1 .Lprod_sync_0
	s_add_i32 s67, s57, 3
	s_lshl_b32 s67, s67, 15
	v_add_u32_e32 v14, s67, v12
	v_add_u32_e32 v15, s67, v13
	global_load_dword v44, v14, s[28:29]
	global_load_dword v48, v15, s[28:29]
	global_load_dword v45, v14, s[34:35]
	global_load_dword v49, v15, s[34:35]
	global_load_dword v46, v14, s[22:23]
	global_load_dword v50, v15, s[22:23]
	global_load_dword v47, v14, s[36:37]
	global_load_dword v51, v15, s[36:37]
	global_load_dword v0, v14, s[22:23] offset:-2048
	global_load_dword v40, v15, s[22:23] offset:-2048

; DI void rwkv_scan_phase(int wv, const Params& P, LAS unsigned char* lds) {
;     ...
;                     if (ck + 1 < nck) { const int cn = ck + 1, buf = cn & 1;
; #pragma unroll
;                         for (int i = 0; i < 3; ++i) { const int pp = pw + 6 * i; if (pp < 16) { const int tt = 2 * pp + hf; const size_t row = (size_t)b * SEQ + cn * RW_T + tt;
.Lprod_half_1:
	s_cmp_gt_i32 s57, 0x1fe
	s_cbranch_scc1 .Lprod_sync_1
	s_add_i32 s67, s57, 1
	s_lshl_b32 s60, s67, 10
	v_add_u32_e32 v58, s60, v10
	s_cmp_gt_i32 s57, 0x1fd
	s_cbranch_scc1 .Lprod_w0_1
	s_waitcnt vmcnt(10)
	s_branch .Lprod_wd_1

; #define LAS __attribute__((address_space(3)))
; DI float bflo(unsigned u) { return __uint_as_float(u << 16); }
; DI float bfhi(unsigned u) { return __uint_as_float(u & 0xffff0000u); }
; template <int CTRL> DI float dpp_f(float v) { return __builtin_bit_cast(float, __builtin_amdgcn_update_dpp(0, __builtin_bit_cast(int, v), CTRL, 0xf, 0xf, true)); }
; DI void rwkv_scan_phase(int wv, const Params& P, LAS unsigned char* lds) {
;     ...
;                         for (int i = 0; i < 3; ++i) { const int pp = pw + 6 * i; if (pp < 16) { const int tt = 2 * pp + hf; const size_t row = (size_t)b * SEQ + cn * RW_T + tt;
;                             const f32x2 k = {bflo(gk[i]), bfhi(gk[i])}, a = {bflo(ga[i]), bfhi(ga[i])}, r = {bflo(gr[i]), bfhi(gr[i])};
;                             const h16x2 lh = __builtin_bit_cast(h16x2, gl[i]);
;                             const f32x2 kr = k * kkw2, kp = k * ((a - 1.f) * kaw2 + 1.f);
;                             const float sp = kr[0] * kr[0] + kr[1] * kr[1], rp = r[0] * kp[0] * rkw2[0] + r[1] * kp[1] * rkw2[1];
;                             const bool odd = lane & 1;
;                             float red = (odd ? rp : sp) + dpp_f<0xB1>(odd ? sp : rp);
;                             red += dpp_f<0x4E>(red); red += dpp_f<0x124>(red); red += dpp_f<0x128>(red);
;                             { auto x = __builtin_amdgcn_permlane16_swap(__float_as_uint(red), __float_as_uint(red), false, false); red = __uint_as_float(x[0]) + __uint_as_float(x[1]); }
;                             const float oth = dpp_f<0xB1>(red); const float ss = odd ? oth : red, rks = odd ? red : oth;
;                             const f32x2 kk = kr * __builtin_amdgcn_rsqf(fmaxf(ss, 1e-24f));
;                             LAS float* d = stg + ((buf * RW_T + tt) * 5) * 64 + 2 * c2;
;                             *(LAS f32x2*)(d) = -kk; *(LAS f32x2*)(d + 64) = (f32x2){__expf((float)lh[0]), __expf((float)lh[1])}; *(LAS f32x2*)(d + 128) = kk * a; *(LAS f32x2*)(d + 192) = kp; *(LAS f32x2*)(d + 256) = r;
;                             if (rg == 0 && c2 == 0) RK[row * 16 + h] = rks;
;                             if (c2 < 8) vst[(buf * RW_T + tt) * 8 + c2] = gv[i]; } }
;                         if (ck + 2 < nck) { RW_LOADG(ck + 2) } }
.Lprod_wd_1:
	v_lshlrev_b32_e32 v64, 16, v25
	v_and_b32_e32 v65, 0xffff0000, v25
	v_pk_add_f32 v[72:73], v[64:65], -1.0 op_sel_hi:[1,0]
	v_lshlrev_b32_e32 v66, 16, v24
	v_and_b32_e32 v67, 0xffff0000, v24
	v_pk_fma_f32 v[72:73], v[6:7], v[72:73], 1.0 op_sel_hi:[1,1,0]
	v_and_b32_e32 v69, 0xffff0000, v26
	v_pk_mul_f32 v[70:71], v[4:5], v[66:67]
	v_pk_mul_f32 v[66:67], v[72:73], v[66:67]
	v_lshlrev_b32_e32 v68, 16, v26
	v_mul_f32_e32 v75, v67, v69
	v_pk_mul_f32 v[72:73], v[70:71], v[70:71]
	v_mul_f32_e32 v74, v66, v68
	v_mul_f32_e32 v75, v9, v75
	v_add_f32_e32 v76, v72, v73
	v_fmac_f32_e32 v75, v8, v74
	v_cndmask_b32_e64 v74, v75, v76, s[8:9]
	v_cndmask_b32_e64 v76, v76, v75, s[8:9]
	v_cvt_f32_f16_e32 v77, v27
	v_cvt_f32_f16_sdwa v78, v27 dst_sel:DWORD dst_unused:UNUSED_PAD src0_sel:WORD_1
	v_add_f32_dpp v76, v76, v74 quad_perm:[1,0,3,2] row_mask:0xf bank_mask:0xf bound_ctrl:1
	v_mul_f32_e32 v77, 0x3fb8aa3b, v77
	s_nop 0
	v_add_f32_dpp v76, v76, v76 quad_perm:[2,3,0,1] row_mask:0xf bank_mask:0xf bound_ctrl:1
	v_exp_f32_e32 v72, v77
	v_mul_f32_e32 v77, 0x3fb8aa3b, v78
	v_add_f32_dpp v76, v76, v76 row_ror:4 row_mask:0xf bank_mask:0xf bound_ctrl:1
	v_exp_f32_e32 v73, v77
	s_nop 0
	v_add_f32_dpp v76, v76, v76 row_ror:8 row_mask:0xf bank_mask:0xf bound_ctrl:1
	v_mov_b32_e32 v74, v76
	s_nop 1
	v_permlane16_swap_b32_e32 v76, v74
	v_add_f32_e32 v76, v76, v74
	s_nop 1
	v_mov_b32_dpp v74, v76 quad_perm:[1,0,3,2] row_mask:0xf bank_mask:0xf bound_ctrl:1
	v_cndmask_b32_e64 v75, v74, v76, s[8:9]
	v_max_f32_e32 v75, v75, v75
	v_max_f32_e32 v75, 0x179abe15, v75
	v_rsq_f32_e32 v42, v75
	v_cndmask_b32_e64 v76, v76, v74, s[8:9]
	s_nop 0
	v_pk_mul_f32 v[70:71], v[70:71], v[42:43] op_sel_hi:[1,0] neg_lo:[0,1] neg_hi:[0,1]
	ds_write_b64 v55, v[72:73] offset:512
	s_nop 0
	v_pk_mul_f32 v[64:65], v[70:71], v[64:65] neg_lo:[1,0] neg_hi:[1,0]
	v_mov_b32_e32 v72, v71
	v_lshlrev_b32_e32 v71, 16, v3
	ds_write_b64 v55, v[64:65] offset:768
	v_and_b32_e32 v73, 0xffff0000, v3
	ds_write_b128 v56, v[70:73]
	v_mov_b32_e32 v60, v76
	v_lshlrev_b32_e32 v64, 16, v29
	v_and_b32_e32 v65, 0xffff0000, v29
	v_pk_add_f32 v[72:73], v[64:65], -1.0 op_sel_hi:[1,0]
	v_lshlrev_b32_e32 v66, 16, v28
	v_and_b32_e32 v67, 0xffff0000, v28
	v_pk_fma_f32 v[72:73], v[6:7], v[72:73], 1.0 op_sel_hi:[1,1,0]
	v_and_b32_e32 v69, 0xffff0000, v30
	v_pk_mul_f32 v[70:71], v[4:5], v[66:67]
	v_pk_mul_f32 v[66:67], v[72:73], v[66:67]
	v_lshlrev_b32_e32 v68, 16, v30
	v_mul_f32_e32 v75, v67, v69
	v_pk_mul_f32 v[72:73], v[70:71], v[70:71]
	v_mul_f32_e32 v74, v66, v68
	v_mul_f32_e32 v75, v9, v75
	v_add_f32_e32 v76, v72, v73
	v_fmac_f32_e32 v75, v8, v74
	v_cndmask_b32_e64 v74, v75, v76, s[8:9]
	v_cndmask_b32_e64 v76, v76, v75, s[8:9]
	v_cvt_f32_f16_e32 v77, v31
	v_cvt_f32_f16_sdwa v78, v31 dst_sel:DWORD dst_unused:UNUSED_PAD src0_sel:WORD_1
	v_add_f32_dpp v76, v76, v74 quad_perm:[1,0,3,2] row_mask:0xf bank_mask:0xf bound_ctrl:1
	v_mul_f32_e32 v77, 0x3fb8aa3b, v77
	s_nop 0
	v_add_f32_dpp v76, v76, v76 quad_perm:[2,3,0,1] row_mask:0xf bank_mask:0xf bound_ctrl:1
	v_exp_f32_e32 v72, v77
	v_mul_f32_e32 v77, 0x3fb8aa3b, v78
	v_add_f32_dpp v76, v76, v76 row_ror:4 row_mask:0xf bank_mask:0xf bound_ctrl:1
	v_exp_f32_e32 v73, v77
	s_nop 0
	v_add_f32_dpp v76, v76, v76 row_ror:8 row_mask:0xf bank_mask:0xf bound_ctrl:1
	v_mov_b32_e32 v74, v76
	s_nop 1
	v_permlane16_swap_b32_e32 v76, v74
	v_add_f32_e32 v76, v76, v74
	s_nop 1
	v_mov_b32_dpp v74, v76 quad_perm:[1,0,3,2] row_mask:0xf bank_mask:0xf bound_ctrl:1
	v_cndmask_b32_e64 v75, v74, v76, s[8:9]
	v_max_f32_e32 v75, v75, v75
	v_max_f32_e32 v75, 0x179abe15, v75
	v_rsq_f32_e32 v42, v75
	v_cndmask_b32_e64 v76, v76, v74, s[8:9]
	s_nop 0
	v_pk_mul_f32 v[70:71], v[70:71], v[42:43] op_sel_hi:[1,0] neg_lo:[0,1] neg_hi:[0,1]
	ds_write_b64 v55, v[72:73] offset:6656
	s_nop 0
	v_pk_mul_f32 v[64:65], v[70:71], v[64:65] neg_lo:[1,0] neg_hi:[1,0]
	v_mov_b32_e32 v72, v71
	v_lshlrev_b32_e32 v71, 16, v43
	ds_write_b64 v55, v[64:65] offset:6912
	v_and_b32_e32 v73, 0xffff0000, v43
	ds_write_b128 v56, v[70:73] offset:6144
	v_mov_b32_e32 v61, v76
	s_mov_b64 exec, s[42:43]
	global_store_dword v58, v60, s[50:51]
	global_store_dword v58, v61, s[50:51] offset:128
	s_mov_b64 exec, -1
	s_cmp_lg_u32 s55, 3
	s_cbranch_scc1 .Lprod_no_rl_1
	s_mov_b32 exec_lo, 0
	ds_write_b64 v57, v[68:69]
	s_mov_b64 exec, -1
.Lprod_no_rl_1:
	s_cmp_gt_i32 s57, 0x1fc
	s_cbranch_scc1 .Lprod_sync_1
	s_add_i32 s67, s57, 3
	s_lshl_b32 s67, s67, 15
	v_add_u32_e32 v14, s67, v12
	v_add_u32_e32 v15, s67, v13
	global_load_dword v24, v14, s[28:29]
	global_load_dword v28, v15, s[28:29]
	global_load_dword v25, v14, s[34:35]
	global_load_dword v29, v15, s[34:35]
	global_load_dword v26, v14, s[22:23]
	global_load_dword v30, v15, s[22:23]
	global_load_dword v27, v14, s[36:37]
	global_load_dword v31, v15, s[36:37]
	global_load_dword v3, v14, s[22:23] offset:-2048
	global_load_dword v43, v15, s[22:23] offset:-2048

; DI void rwkv_scan_phase(int wv, const Params& P, LAS unsigned char* lds) {
;     ...
;             const int ch = h * 64 + lane;
;             const float kkw = P.in[35][ch], kaw = P.in[36][ch], rkw = P.in[37][ch];
;             const int hf = lane >> 5, c2 = lane & 31, chp = h * 64 + 2 * c2;
;             const f32x2 kkw2 = *(const f32x2*)(P.in[35] + chp), kaw2 = *(const f32x2*)(P.in[36] + chp), rkw2 = *(const f32x2*)(P.in[37] + chp);
;             unsigned gk[3], ga[3], gr[3], gl[3]; float gv[3];
;     ...
;             RW_LOADG(0)
.Lprod_flusher:
	s_and_b32 s55, s55, 1
	s_and_b32 s67, s46, 7
	s_bfe_u32 s59, s46, 0x40003
	s_lshl_b32 s61, s59, 6
	v_mbcnt_lo_u32_b32 v0, -1, 0
	v_mbcnt_hi_u32_b32 v0, -1, v0
	v_and_b32_e32 v1, 15, v0
	v_lshrrev_b32_e32 v34, 4, v0
	v_lshl_add_u32 v35, v1, 2, s61
	v_lshlrev_b32_e32 v24, 2, v35
	global_load_dwordx4 v[4:7], v24, s[26:27]
	s_lshr_b32 s60, s46, 7
	s_lshl_b32 s60, s60, 13
	s_lshl_b32 s66, s55, 3
	s_add_i32 s60, s60, s66
	v_add_u32_e32 v25, s60, v34
	v_lshlrev_b32_e32 v26, 11, v25
	v_lshl_add_u32 v12, v35, 1, v26
	v_add_u32_e32 v13, 0x2000, v12
	s_lshl_b32 s62, s67, 3
	s_add_i32 s62, s62, s61
	v_mov_b32_e32 v27, s62
	v_lshl_add_u32 v14, v27, 1, v26
	v_add_u32_e32 v15, 0x2000, v14
	v_add_u32_e32 v25, s66, v34
	v_mul_u32_u24_e32 v2, 0xc00, v25
	v_lshl_add_u32 v2, v1, 4, v2
	v_add_u32_e32 v2, 0x400, v2
	v_and_b32_e32 v36, 7, v0
	v_lshrrev_b32_e32 v37, 3, v0
	v_add_u32_e32 v37, s66, v37
	v_lshlrev_b32_e32 v3, 9, v37
	v_lshl_add_u32 v3, v36, 6, v3
	v_add_u32_e32 v3, 0x18000, v3
	s_lshr_b32 s60, s46, 7
	s_lshl_b32 s60, s60, 13
	v_add_u32_e32 v37, s60, v37
	v_lshlrev_b32_e32 v37, 11, v37
	v_add_u32_e32 v38, s62, v36
	v_lshl_add_u32 v20, v38, 1, v37
	s_mov_b32 s57, -1
	s_mov_b32 s69, 0
	s_mov_b32 s67, 0
	s_waitcnt vmcnt(0)
	v_add_u32_e32 v34, s67, v12
	v_add_u32_e32 v35, s67, v13
	global_load_dwordx2 v[44:45], v34, s[28:29]
	global_load_dwordx2 v[52:53], v35, s[28:29]
	global_load_dwordx2 v[46:47], v34, s[34:35]
	global_load_dwordx2 v[54:55], v35, s[34:35]
	v_add_u32_e32 v34, s67, v14
	v_add_u32_e32 v35, s67, v15
	global_load_dwordx4 v[48:51], v34, s[30:31]
	global_load_dwordx4 v[56:59], v35, s[30:31]
	s_mov_b32 s67, 0x8000
	v_add_u32_e32 v34, s67, v12
	v_add_u32_e32 v35, s67, v13
	global_load_dwordx2 v[60:61], v34, s[28:29]
	global_load_dwordx2 v[68:69], v35, s[28:29]
	global_load_dwordx2 v[62:63], v34, s[34:35]
	global_load_dwordx2 v[70:71], v35, s[34:35]
	v_add_u32_e32 v34, s67, v14
	v_add_u32_e32 v35, s67, v15
	global_load_dwordx4 v[64:67], v34, s[30:31]
	global_load_dwordx4 v[72:75], v35, s[30:31]

.Lflush_ld_0:
	s_cmp_gt_i32 s57, 0x1fc
	s_cbranch_scc1 .Lflush_sync_0
	s_add_i32 s67, s57, 3
	s_lshl_b32 s67, s67, 15
	v_add_u32_e32 v34, s67, v12
	v_add_u32_e32 v35, s67, v13
	global_load_dwordx2 v[44:45], v34, s[28:29]
	global_load_dwordx2 v[52:53], v35, s[28:29]
	global_load_dwordx2 v[46:47], v34, s[34:35]
	global_load_dwordx2 v[54:55], v35, s[34:35]
	v_add_u32_e32 v34, s67, v14
	v_add_u32_e32 v35, s67, v15
	global_load_dwordx4 v[48:51], v34, s[30:31]
	global_load_dwordx4 v[56:59], v35, s[30:31]

.Lflush_ld_1:
	s_cmp_gt_i32 s57, 0x1fc
	s_cbranch_scc1 .Lflush_sync_1
	s_add_i32 s67, s57, 3
	s_lshl_b32 s67, s67, 15
	v_add_u32_e32 v34, s67, v12
	v_add_u32_e32 v35, s67, v13
	global_load_dwordx2 v[60:61], v34, s[28:29]
	global_load_dwordx2 v[68:69], v35, s[28:29]
	global_load_dwordx2 v[62:63], v34, s[34:35]
	global_load_dwordx2 v[70:71], v35, s[34:35]
	v_add_u32_e32 v34, s67, v14
	v_add_u32_e32 v35, s67, v15
	global_load_dwordx4 v[64:67], v34, s[30:31]
	global_load_dwordx4 v[72:75], v35, s[30:31]
